# cache-policy selection: the streamed K/V cache rows of the decode loop loaded sc1 nt (agent scope, non-temporal) instead of nt
# baseline (speedup 1.0000x reference)
; __device__ __forceinline__ void sb_decode_stream(Frame& F, unsigned* qctr, int base, int limit) {
;     ...
;     { const unsigned v = __hip_atomic_fetch_add(qctr, 1u, __ATOMIC_RELAXED, __HIP_MEMORY_SCOPE_AGENT);
;       it = (int)(__builtin_amdgcn_readfirstlane(v) >> 6); if (it >= limit) return; it += base; }
;     f32x4 A[16], B[16], q4;
;     size_t cb;
;     { const int b = it >> 11, h = it & 7, p0 = ((it >> 3) & 255) * 64;
;       const int page = PT[b * NPAGES + (p0 >> 7)];
;       cb = (((size_t)page * PAGE + (p0 & 127)) * NH + h) * HD + lo;
;       q4 = *(const f32x4*)(SSP(S_PROJ) + (size_t)b * IN_COLS + h * HD + 4 * l32);
; #pragma unroll
;       for (int i = 0; i < 16; ++i) A[i] = __builtin_nontemporal_load((const f32x4*)(CK + cb + (size_t)(2 * i) * (NH * HD)));
; #pragma unroll
;       for (int i = 0; i < 16; ++i) B[i] = __builtin_nontemporal_load((const f32x4*)(CK + cb + (size_t)(32 + 2 * i) * (NH * HD))); }
.Ldqa_sh1:
	s_barrier
	ds_read_b32 v201, v200
	s_xor_b32 s37, s37, 4
	s_waitcnt lgkmcnt(0)
	v_readfirstlane_b32 s2, v201
	s_nop 0
	s_lshr_b32 s72, s2, 6
	s_cmp_ge_u32 s72, 0x1800
	s_cbranch_scc1 .Ldqa_exit
	s_add_u32 s72, s72, s94
	s_min_u32 s72, s72, 0x17ff
	s_mov_b32 s74, s72
	s_mov_b32 s75, 0
	s_waitcnt lgkmcnt(0)
	s_lshr_b32 s6, s72, 11
	s_and_b32 s7, s72, 7
	s_bfe_u32 s8, s72, 0x80003
	s_lshl_b32 s9, s6, 7
	s_lshr_b32 s10, s8, 1
	s_or_b32 s9, s9, s10
	s_lshl_b32 s9, s9, 2
	s_lshl_b32 s10, s7, 2
	s_load_dword s29, s[54:55], s9
	s_load_dword s30, s[56:57], s10
	s_waitcnt lgkmcnt(0)
	s_mov_b32 s12, s29
	s_mov_b32 s13, 0
	s_lshl_b64 s[12:13], s[12:13], 19
	s_and_b32 s14, s8, 1
	s_lshl_b32 s14, s14, 18
	s_lshl_b32 s15, s7, 9
	s_or_b32 s14, s14, s15
	s_or_b32 s80, s12, s14
	s_mov_b32 s81, s13
	s_add_u32 s64, s50, s80
	s_addc_u32 s65, s51, s81
	s_mul_i32 s16, s6, 0x7040
	s_add_u32 s16, s16, s15
	s_add_u32 s16, s60, s16
	s_addc_u32 s17, s61, 0
	global_load_dwordx4 v[156:159], v193, s[16:17]
	global_load_dwordx4 v[4:7], v187, s[64:65] sc1 nt
	s_add_u32 s64, s64, 0x2000
	s_addc_u32 s65, s65, 0
	global_load_dwordx4 v[8:11], v187, s[64:65] sc1 nt
	s_add_u32 s64, s64, 0x2000
	s_addc_u32 s65, s65, 0
	global_load_dwordx4 v[12:15], v187, s[64:65] sc1 nt
	s_add_u32 s64, s64, 0x2000
	s_addc_u32 s65, s65, 0
	global_load_dwordx4 v[16:19], v187, s[64:65] sc1 nt
	s_add_u32 s64, s64, 0x2000
	s_addc_u32 s65, s65, 0
	global_load_dwordx4 v[20:23], v187, s[64:65] sc1 nt
	s_add_u32 s64, s64, 0x2000
	s_addc_u32 s65, s65, 0
	global_load_dwordx4 v[24:27], v187, s[64:65] sc1 nt
	s_add_u32 s64, s64, 0x2000
	s_addc_u32 s65, s65, 0
	global_load_dwordx4 v[28:31], v187, s[64:65] sc1 nt
	s_add_u32 s64, s64, 0x2000
	s_addc_u32 s65, s65, 0
	global_load_dwordx4 v[32:35], v187, s[64:65] sc1 nt
	s_add_u32 s64, s64, 0x2000
	s_addc_u32 s65, s65, 0
	global_load_dwordx4 v[36:39], v187, s[64:65] sc1 nt
	s_add_u32 s64, s64, 0x2000
	s_addc_u32 s65, s65, 0
	global_load_dwordx4 v[40:43], v187, s[64:65] sc1 nt
	s_add_u32 s64, s64, 0x2000
	s_addc_u32 s65, s65, 0
	global_load_dwordx4 v[44:47], v187, s[64:65] sc1 nt
	s_add_u32 s64, s64, 0x2000
	s_addc_u32 s65, s65, 0
	global_load_dwordx4 v[48:51], v187, s[64:65] sc1 nt
	s_add_u32 s64, s64, 0x2000
	s_addc_u32 s65, s65, 0
	global_load_dwordx4 v[52:55], v187, s[64:65] sc1 nt
	s_add_u32 s64, s64, 0x2000
	s_addc_u32 s65, s65, 0
	global_load_dwordx4 v[56:59], v187, s[64:65] sc1 nt
	s_add_u32 s64, s64, 0x2000
	s_addc_u32 s65, s65, 0
	global_load_dwordx4 v[60:63], v187, s[64:65] sc1 nt
	s_add_u32 s64, s64, 0x2000
	s_addc_u32 s65, s65, 0
	global_load_dwordx4 v[64:67], v187, s[64:65] sc1 nt
	s_add_u32 s64, s64, 0x2000
	s_addc_u32 s65, s65, 0
	global_load_dwordx4 v[68:71], v187, s[64:65] sc1 nt
	s_add_u32 s64, s64, 0x2000
	s_addc_u32 s65, s65, 0
	global_load_dwordx4 v[72:75], v187, s[64:65] sc1 nt
	s_add_u32 s64, s64, 0x2000
	s_addc_u32 s65, s65, 0
	global_load_dwordx4 v[76:79], v187, s[64:65] sc1 nt
	s_add_u32 s64, s64, 0x2000
	s_addc_u32 s65, s65, 0
	global_load_dwordx4 v[80:83], v187, s[64:65] sc1 nt
	s_add_u32 s64, s64, 0x2000
	s_addc_u32 s65, s65, 0
	global_load_dwordx4 v[84:87], v187, s[64:65] sc1 nt
	s_add_u32 s64, s64, 0x2000
	s_addc_u32 s65, s65, 0
	global_load_dwordx4 v[88:91], v187, s[64:65] sc1 nt
	s_add_u32 s64, s64, 0x2000
	s_addc_u32 s65, s65, 0
	global_load_dwordx4 v[92:95], v187, s[64:65] sc1 nt
	s_add_u32 s64, s64, 0x2000
	s_addc_u32 s65, s65, 0
	global_load_dwordx4 v[96:99], v187, s[64:65] sc1 nt
	s_add_u32 s64, s64, 0x2000
	s_addc_u32 s65, s65, 0
	global_load_dwordx4 v[100:103], v187, s[64:65] sc1 nt
	s_add_u32 s64, s64, 0x2000
	s_addc_u32 s65, s65, 0
	global_load_dwordx4 v[104:107], v187, s[64:65] sc1 nt
	s_add_u32 s64, s64, 0x2000
	s_addc_u32 s65, s65, 0
	global_load_dwordx4 v[108:111], v187, s[64:65] sc1 nt
	s_add_u32 s64, s64, 0x2000
	s_addc_u32 s65, s65, 0
	global_load_dwordx4 v[112:115], v187, s[64:65] sc1 nt
	s_add_u32 s64, s64, 0x2000
	s_addc_u32 s65, s65, 0
	global_load_dwordx4 v[116:119], v187, s[64:65] sc1 nt
	s_add_u32 s64, s64, 0x2000
	s_addc_u32 s65, s65, 0
	global_load_dwordx4 v[120:123], v187, s[64:65] sc1 nt
	s_add_u32 s64, s64, 0x2000
	s_addc_u32 s65, s65, 0
	global_load_dwordx4 v[124:127], v187, s[64:65] sc1 nt
	s_add_u32 s64, s64, 0x2000
	s_addc_u32 s65, s65, 0
	global_load_dwordx4 v[128:131], v187, s[64:65] sc1 nt
	s_add_u32 s64, s64, 0x2000
	s_addc_u32 s65, s65, 0
	global_load_dword v194, v189, s[58:59]
	global_load_dword v195, v189, s[58:59]

; __device__ __forceinline__ void sb_decode_stream(Frame& F, unsigned* qctr, int base, int limit) {
;     ...
;         const int bh = ((it >> 11) << 3) | (it & 7), blk = (it >> 3) & 255, h = it & 7;
;         const unsigned vn = __hip_atomic_fetch_add(qctr, 1u, __ATOMIC_RELAXED, __HIP_MEMORY_SCOPE_AGENT);
;         const float k2 = kin(12)[h] * 1.4426950408889634f;
;         int zi = 0;
;     ...
;         DEC_SCORES(A, 0);
; #pragma unroll
;         for (int i = 0; i < 16; ++i) A[i] = __builtin_nontemporal_load((const f32x4*)(CV + cb + (size_t)(2 * i) * (NH * HD)));
;         DEC_SCORES(B, 1);
;     ...
; #pragma unroll
;         for (int i = 0; i < 16; ++i) B[i] = __builtin_nontemporal_load((const f32x4*)(CV + cb + (size_t)(32 + 2 * i) * (NH * HD)));
.Ldqa_fetched:
	s_nop 0
	s_add_u32 s66, s52, s68
	s_addc_u32 s67, s53, s69
	s_lshr_b32 s18, s72, 11
	s_lshl_b32 s18, s18, 3
	s_and_b32 s19, s72, 7
	s_or_b32 s18, s18, s19
	s_lshl_b32 s18, s18, 8
	s_bfe_u32 s19, s72, 0x80003
	s_or_b32 s18, s18, s19
	s_mul_i32 s18, s18, 0x210
	s_add_u32 s70, s62, s18
	s_addc_u32 s71, s63, 0
	v_mov_b32_e32 v192, s28
	v_mul_f32_e32 v192, 0x3fb8aa3b, v192
	s_waitcnt vmcnt(34)
	v_mov_b32_e32 v152, v156
	v_mov_b32_e32 v153, v157
	v_mov_b32_e32 v154, v158
	v_mov_b32_e32 v155, v159
	v_pk_mul_f32 v[148:149], v[4:5], v[152:153]
	v_pk_fma_f32 v[148:149], v[6:7], v[154:155], v[148:149]
	global_load_dwordx4 v[4:7], v187, s[66:67] sc1 nt
	s_add_u32 s66, s66, 0x2000
	s_addc_u32 s67, s67, 0
	v_add_f32_e32 v132, v148, v149
	s_waitcnt vmcnt(34)
	v_pk_mul_f32 v[150:151], v[8:9], v[152:153]
	v_pk_fma_f32 v[150:151], v[10:11], v[154:155], v[150:151]
	global_load_dwordx4 v[8:11], v187, s[66:67] sc1 nt
	s_add_u32 s66, s66, 0x2000
	s_addc_u32 s67, s67, 0
	v_add_f32_e32 v133, v150, v151
	s_waitcnt vmcnt(34)
	v_pk_mul_f32 v[148:149], v[12:13], v[152:153]
	v_pk_fma_f32 v[148:149], v[14:15], v[154:155], v[148:149]
	global_load_dwordx4 v[12:15], v187, s[66:67] sc1 nt
	s_add_u32 s66, s66, 0x2000
	s_addc_u32 s67, s67, 0
	v_add_f32_e32 v134, v148, v149
	s_waitcnt vmcnt(34)
	v_pk_mul_f32 v[150:151], v[16:17], v[152:153]
	v_pk_fma_f32 v[150:151], v[18:19], v[154:155], v[150:151]
	global_load_dwordx4 v[16:19], v187, s[66:67] sc1 nt
	s_add_u32 s66, s66, 0x2000
	s_addc_u32 s67, s67, 0
	v_add_f32_e32 v135, v150, v151
	s_waitcnt vmcnt(34)
	v_pk_mul_f32 v[148:149], v[20:21], v[152:153]
	v_pk_fma_f32 v[148:149], v[22:23], v[154:155], v[148:149]
	global_load_dwordx4 v[20:23], v187, s[66:67] sc1 nt
	s_add_u32 s66, s66, 0x2000
	s_addc_u32 s67, s67, 0
	v_add_f32_e32 v136, v148, v149
	s_waitcnt vmcnt(34)
	v_pk_mul_f32 v[150:151], v[24:25], v[152:153]
	v_pk_fma_f32 v[150:151], v[26:27], v[154:155], v[150:151]
	global_load_dwordx4 v[24:27], v187, s[66:67] sc1 nt
	s_add_u32 s66, s66, 0x2000
	s_addc_u32 s67, s67, 0
	v_add_f32_e32 v137, v150, v151
	s_waitcnt vmcnt(34)
	v_pk_mul_f32 v[148:149], v[28:29], v[152:153]
	v_pk_fma_f32 v[148:149], v[30:31], v[154:155], v[148:149]
	global_load_dwordx4 v[28:31], v187, s[66:67] sc1 nt
	s_add_u32 s66, s66, 0x2000
	s_addc_u32 s67, s67, 0
	v_add_f32_e32 v138, v148, v149
	s_waitcnt vmcnt(34)
	v_pk_mul_f32 v[150:151], v[32:33], v[152:153]
	v_pk_fma_f32 v[150:151], v[34:35], v[154:155], v[150:151]
	global_load_dwordx4 v[32:35], v187, s[66:67] sc1 nt
	s_add_u32 s66, s66, 0x2000
	s_addc_u32 s67, s67, 0
	v_add_f32_e32 v139, v150, v151
	s_waitcnt vmcnt(34)
	v_pk_mul_f32 v[148:149], v[36:37], v[152:153]
	v_pk_fma_f32 v[148:149], v[38:39], v[154:155], v[148:149]
	global_load_dwordx4 v[36:39], v187, s[66:67] sc1 nt
	s_add_u32 s66, s66, 0x2000
	s_addc_u32 s67, s67, 0
	v_add_f32_e32 v140, v148, v149
	s_waitcnt vmcnt(34)
	v_pk_mul_f32 v[150:151], v[40:41], v[152:153]
	v_pk_fma_f32 v[150:151], v[42:43], v[154:155], v[150:151]
	global_load_dwordx4 v[40:43], v187, s[66:67] sc1 nt
	s_add_u32 s66, s66, 0x2000
	s_addc_u32 s67, s67, 0
	v_add_f32_e32 v141, v150, v151
	s_waitcnt vmcnt(34)
	v_pk_mul_f32 v[148:149], v[44:45], v[152:153]
	v_pk_fma_f32 v[148:149], v[46:47], v[154:155], v[148:149]
	global_load_dwordx4 v[44:47], v187, s[66:67] sc1 nt
	s_add_u32 s66, s66, 0x2000
	s_addc_u32 s67, s67, 0
	v_add_f32_e32 v142, v148, v149
	s_waitcnt vmcnt(34)
	v_pk_mul_f32 v[150:151], v[48:49], v[152:153]
	v_pk_fma_f32 v[150:151], v[50:51], v[154:155], v[150:151]
	global_load_dwordx4 v[48:51], v187, s[66:67] sc1 nt
	s_add_u32 s66, s66, 0x2000
	s_addc_u32 s67, s67, 0
	v_add_f32_e32 v143, v150, v151
	s_waitcnt vmcnt(34)
	v_pk_mul_f32 v[148:149], v[52:53], v[152:153]
	v_pk_fma_f32 v[148:149], v[54:55], v[154:155], v[148:149]
	global_load_dwordx4 v[52:55], v187, s[66:67] sc1 nt
	s_add_u32 s66, s66, 0x2000
	s_addc_u32 s67, s67, 0
	v_add_f32_e32 v144, v148, v149
	s_waitcnt vmcnt(34)
	v_pk_mul_f32 v[150:151], v[56:57], v[152:153]
	v_pk_fma_f32 v[150:151], v[58:59], v[154:155], v[150:151]
	global_load_dwordx4 v[56:59], v187, s[66:67] sc1 nt
	s_add_u32 s66, s66, 0x2000
	s_addc_u32 s67, s67, 0
	v_add_f32_e32 v145, v150, v151
	s_waitcnt vmcnt(34)
	v_pk_mul_f32 v[148:149], v[60:61], v[152:153]
	v_pk_fma_f32 v[148:149], v[62:63], v[154:155], v[148:149]
	global_load_dwordx4 v[60:63], v187, s[66:67] sc1 nt
	s_add_u32 s66, s66, 0x2000
	s_addc_u32 s67, s67, 0
	v_add_f32_e32 v146, v148, v149
	s_waitcnt vmcnt(34)
	v_pk_mul_f32 v[150:151], v[64:65], v[152:153]
	v_pk_fma_f32 v[150:151], v[66:67], v[154:155], v[150:151]
	global_load_dwordx4 v[64:67], v187, s[66:67] sc1 nt
	s_add_u32 s66, s66, 0x2000
	s_addc_u32 s67, s67, 0
	v_add_f32_e32 v147, v150, v151
	s_barrier
; __device__ __forceinline__ void sb_decode_stream(Frame& F, unsigned* qctr, int base, int limit) {
;     ...
;         DEC_SCORES(A, 0);
; #pragma unroll
;         for (int i = 0; i < 16; ++i) A[i] = __builtin_nontemporal_load((const f32x4*)(CV + cb + (size_t)(2 * i) * (NH * HD)));
;         DEC_SCORES(B, 1);
;     ...
; #pragma unroll
;         for (int i = 0; i < 16; ++i) B[i] = __builtin_nontemporal_load((const f32x4*)(CV + cb + (size_t)(32 + 2 * i) * (NH * HD)));
	v_add_f32_dpp v132, v132, v132 row_ror:8 row_mask:0xf bank_mask:0x3
	v_add_f32_dpp v133, v133, v133 row_ror:8 row_mask:0xf bank_mask:0x3
	v_add_f32_dpp v134, v134, v134 row_ror:8 row_mask:0xf bank_mask:0x3
	v_add_f32_dpp v135, v135, v135 row_ror:8 row_mask:0xf bank_mask:0x3
	v_add_f32_dpp v136, v136, v136 row_ror:8 row_mask:0xf bank_mask:0x3
	v_add_f32_dpp v137, v137, v137 row_ror:8 row_mask:0xf bank_mask:0x3
	v_add_f32_dpp v138, v138, v138 row_ror:8 row_mask:0xf bank_mask:0x3
	v_add_f32_dpp v139, v139, v139 row_ror:8 row_mask:0xf bank_mask:0x3
	v_add_f32_dpp v132, v140, v140 row_ror:8 row_mask:0xf bank_mask:0xc
	v_add_f32_dpp v133, v141, v141 row_ror:8 row_mask:0xf bank_mask:0xc
	v_add_f32_dpp v134, v142, v142 row_ror:8 row_mask:0xf bank_mask:0xc
	v_add_f32_dpp v135, v143, v143 row_ror:8 row_mask:0xf bank_mask:0xc
	v_add_f32_dpp v136, v144, v144 row_ror:8 row_mask:0xf bank_mask:0xc
	v_add_f32_dpp v137, v145, v145 row_ror:8 row_mask:0xf bank_mask:0xc
	v_add_f32_dpp v138, v146, v146 row_ror:8 row_mask:0xf bank_mask:0xc
	v_add_f32_dpp v139, v147, v147 row_ror:8 row_mask:0xf bank_mask:0xc
	v_add_f32_dpp v132, v132, v132 row_ror:12 row_mask:0xf bank_mask:0x5
	v_add_f32_dpp v133, v133, v133 row_ror:12 row_mask:0xf bank_mask:0x5
	v_add_f32_dpp v134, v134, v134 row_ror:12 row_mask:0xf bank_mask:0x5
	v_add_f32_dpp v135, v135, v135 row_ror:12 row_mask:0xf bank_mask:0x5
	v_add_f32_dpp v132, v136, v136 row_ror:4 row_mask:0xf bank_mask:0xa
	v_add_f32_dpp v133, v137, v137 row_ror:4 row_mask:0xf bank_mask:0xa
	v_add_f32_dpp v134, v138, v138 row_ror:4 row_mask:0xf bank_mask:0xa
	v_add_f32_dpp v135, v139, v139 row_ror:4 row_mask:0xf bank_mask:0xa
	v_add_f32_dpp v140, v132, v132 quad_perm:[2,3,0,1] row_mask:0xf bank_mask:0xf
	v_add_f32_dpp v142, v134, v134 quad_perm:[2,3,0,1] row_mask:0xf bank_mask:0xf
	v_add_f32_dpp v141, v133, v133 quad_perm:[2,3,0,1] row_mask:0xf bank_mask:0xf
	v_add_f32_dpp v143, v135, v135 quad_perm:[2,3,0,1] row_mask:0xf bank_mask:0xf
	v_cndmask_b32_e64 v132, v140, v142, s[76:77]
	v_cndmask_b32_e64 v133, v141, v143, s[76:77]
	s_nop 0
	v_add_f32_dpp v196, v132, v132 quad_perm:[1,0,3,2] row_mask:0xf bank_mask:0xf
	v_add_f32_dpp v197, v133, v133 quad_perm:[1,0,3,2] row_mask:0xf bank_mask:0xf
	v_cndmask_b32_e64 v176, v196, v197, s[78:79]
	s_waitcnt vmcnt(34)
	v_pk_mul_f32 v[148:149], v[68:69], v[152:153]
	v_pk_fma_f32 v[148:149], v[70:71], v[154:155], v[148:149]
	global_load_dwordx4 v[68:71], v187, s[66:67] sc1 nt
	s_add_u32 s66, s66, 0x2000
	s_addc_u32 s67, s67, 0
	v_add_f32_e32 v132, v148, v149
	s_waitcnt vmcnt(34)
	v_pk_mul_f32 v[150:151], v[72:73], v[152:153]
	v_pk_fma_f32 v[150:151], v[74:75], v[154:155], v[150:151]
	global_load_dwordx4 v[72:75], v187, s[66:67] sc1 nt
	s_add_u32 s66, s66, 0x2000
	s_addc_u32 s67, s67, 0
	v_add_f32_e32 v133, v150, v151
	s_waitcnt vmcnt(34)
	v_pk_mul_f32 v[148:149], v[76:77], v[152:153]
	v_pk_fma_f32 v[148:149], v[78:79], v[154:155], v[148:149]
	global_load_dwordx4 v[76:79], v187, s[66:67] sc1 nt
	s_add_u32 s66, s66, 0x2000
	s_addc_u32 s67, s67, 0
	v_add_f32_e32 v134, v148, v149
	s_waitcnt vmcnt(34)
	v_pk_mul_f32 v[150:151], v[80:81], v[152:153]
	v_pk_fma_f32 v[150:151], v[82:83], v[154:155], v[150:151]
	global_load_dwordx4 v[80:83], v187, s[66:67] sc1 nt
	s_add_u32 s66, s66, 0x2000
	s_addc_u32 s67, s67, 0
	v_add_f32_e32 v135, v150, v151
	s_waitcnt vmcnt(34)
	v_pk_mul_f32 v[148:149], v[84:85], v[152:153]
	v_pk_fma_f32 v[148:149], v[86:87], v[154:155], v[148:149]
	global_load_dwordx4 v[84:87], v187, s[66:67] sc1 nt
	s_add_u32 s66, s66, 0x2000
	s_addc_u32 s67, s67, 0
	v_add_f32_e32 v136, v148, v149
	s_waitcnt vmcnt(34)
	v_pk_mul_f32 v[150:151], v[88:89], v[152:153]
	v_pk_fma_f32 v[150:151], v[90:91], v[154:155], v[150:151]
	global_load_dwordx4 v[88:91], v187, s[66:67] sc1 nt
	s_add_u32 s66, s66, 0x2000
	s_addc_u32 s67, s67, 0
	v_add_f32_e32 v137, v150, v151
	s_waitcnt vmcnt(34)
	v_pk_mul_f32 v[148:149], v[92:93], v[152:153]
	v_pk_fma_f32 v[148:149], v[94:95], v[154:155], v[148:149]
	global_load_dwordx4 v[92:95], v187, s[66:67] sc1 nt
	s_add_u32 s66, s66, 0x2000
	s_addc_u32 s67, s67, 0
	v_add_f32_e32 v138, v148, v149
	s_waitcnt vmcnt(34)
	v_pk_mul_f32 v[150:151], v[96:97], v[152:153]
	v_pk_fma_f32 v[150:151], v[98:99], v[154:155], v[150:151]
	global_load_dwordx4 v[96:99], v187, s[66:67] sc1 nt
	s_add_u32 s66, s66, 0x2000
	s_addc_u32 s67, s67, 0
	v_add_f32_e32 v139, v150, v151
	s_waitcnt vmcnt(34)
	v_pk_mul_f32 v[148:149], v[100:101], v[152:153]
	v_pk_fma_f32 v[148:149], v[102:103], v[154:155], v[148:149]
	global_load_dwordx4 v[100:103], v187, s[66:67] sc1 nt
	s_add_u32 s66, s66, 0x2000
	s_addc_u32 s67, s67, 0
	v_add_f32_e32 v140, v148, v149
	s_waitcnt vmcnt(34)
	v_pk_mul_f32 v[150:151], v[104:105], v[152:153]
	v_pk_fma_f32 v[150:151], v[106:107], v[154:155], v[150:151]
	global_load_dwordx4 v[104:107], v187, s[66:67] sc1 nt
	s_add_u32 s66, s66, 0x2000
	s_addc_u32 s67, s67, 0
	v_add_f32_e32 v141, v150, v151
	s_waitcnt vmcnt(34)
	v_pk_mul_f32 v[148:149], v[108:109], v[152:153]
	v_pk_fma_f32 v[148:149], v[110:111], v[154:155], v[148:149]
	global_load_dwordx4 v[108:111], v187, s[66:67] sc1 nt
	s_add_u32 s66, s66, 0x2000
	s_addc_u32 s67, s67, 0
	v_add_f32_e32 v142, v148, v149
	s_waitcnt vmcnt(34)
	v_pk_mul_f32 v[150:151], v[112:113], v[152:153]
	v_pk_fma_f32 v[150:151], v[114:115], v[154:155], v[150:151]
	global_load_dwordx4 v[112:115], v187, s[66:67] sc1 nt
	s_add_u32 s66, s66, 0x2000
	s_addc_u32 s67, s67, 0
	v_add_f32_e32 v143, v150, v151
	s_waitcnt vmcnt(34)
	v_pk_mul_f32 v[148:149], v[116:117], v[152:153]
	v_pk_fma_f32 v[148:149], v[118:119], v[154:155], v[148:149]
	global_load_dwordx4 v[116:119], v187, s[66:67] sc1 nt
	s_add_u32 s66, s66, 0x2000
	s_addc_u32 s67, s67, 0
	v_add_f32_e32 v144, v148, v149
	s_waitcnt vmcnt(34)
	v_pk_mul_f32 v[150:151], v[120:121], v[152:153]
	v_pk_fma_f32 v[150:151], v[122:123], v[154:155], v[150:151]
	global_load_dwordx4 v[120:123], v187, s[66:67] sc1 nt
	s_add_u32 s66, s66, 0x2000
	s_addc_u32 s67, s67, 0
	v_add_f32_e32 v145, v150, v151
	s_waitcnt vmcnt(34)
	v_pk_mul_f32 v[148:149], v[124:125], v[152:153]
	v_pk_fma_f32 v[148:149], v[126:127], v[154:155], v[148:149]
	global_load_dwordx4 v[124:127], v187, s[66:67] sc1 nt
	s_add_u32 s66, s66, 0x2000
	s_addc_u32 s67, s67, 0
	v_add_f32_e32 v146, v148, v149
	s_waitcnt vmcnt(34)
	v_pk_mul_f32 v[150:151], v[128:129], v[152:153]
	v_pk_fma_f32 v[150:151], v[130:131], v[154:155], v[150:151]
	global_load_dwordx4 v[128:131], v187, s[66:67] sc1 nt
	s_add_u32 s66, s66, 0x2000
	s_addc_u32 s67, s67, 0
	v_add_f32_e32 v147, v150, v151
	s_waitcnt vmcnt(32)
	v_readfirstlane_b32 s2, v191
	v_mov_b32_e32 v200, s37
	s_cmp_eq_u32 s94, 0
	s_cbranch_scc0 .Ldqa_sh2
	v_mov_b32_e32 v201, s2
	ds_write_b32 v200, v201
	s_waitcnt lgkmcnt(0)
; __device__ __forceinline__ void sb_decode_stream(Frame& F, unsigned* qctr, int base, int limit) {
;     ...
;         const float z = __builtin_bit_cast(float, zi);
;         const float e = __builtin_amdgcn_exp2f(-(z * k1 + k2));
;         const float be = __builtin_amdgcn_rcpf(1.0f + e), m = 1.0f - be;
;         float s = m;
; #pragma unroll
;         for (int o = 1; o < 64; o <<= 1) { const float t = __shfl_down(s, o); if (lane + o < 64) s *= t; }
;         const float tot = __shfl(s, 0);
;         const float sx = __shfl_down(s, 1);
;         const float a = be * (lane < 63 ? sx : 1.0f);
;         int itn = (int)(__builtin_amdgcn_readfirstlane(vn) >> 6); const bool more = itn < limit; itn = more ? itn + base : it;
;         const int bn = itn >> 11, hn = itn & 7, p0n = ((itn >> 3) & 255) * 64;
;         const int pagen = PT[bn * NPAGES + (p0n >> 7)];
;         const size_t cbn = (((size_t)pagen * PAGE + (p0n & 127)) * NH + hn) * HD + lo;
;         const size_t stepn = more ? (size_t)(NH * HD) : 0;
.Ldqa_sh2:
	s_barrier
	ds_read_b32 v201, v200
	s_xor_b32 s37, s37, 4
	s_waitcnt lgkmcnt(0)
	v_readfirstlane_b32 s2, v201
	s_nop 0
	s_lshr_b32 s73, s2, 6
	s_cmp_lt_u32 s73, 0x1800
	s_cselect_b32 s31, 1, 0
	s_add_u32 s73, s73, s94
	s_min_u32 s73, s73, 0x17ff
	s_cmp_eq_u32 s31, 1
	s_cselect_b32 s73, s73, s72
	s_lshr_b32 s6, s73, 11
	s_and_b32 s7, s73, 7
	s_bfe_u32 s8, s73, 0x80003
	s_lshl_b32 s9, s6, 7
	s_lshr_b32 s10, s8, 1
	s_or_b32 s9, s9, s10
	s_lshl_b32 s9, s9, 2
	s_lshl_b32 s10, s7, 2
	s_load_dword s29, s[54:55], s9
	s_load_dword s30, s[56:57], s10
	v_add_f32_dpp v132, v132, v132 row_ror:8 row_mask:0xf bank_mask:0x3
	v_add_f32_dpp v133, v133, v133 row_ror:8 row_mask:0xf bank_mask:0x3
	v_add_f32_dpp v134, v134, v134 row_ror:8 row_mask:0xf bank_mask:0x3
	v_add_f32_dpp v135, v135, v135 row_ror:8 row_mask:0xf bank_mask:0x3
	v_add_f32_dpp v136, v136, v136 row_ror:8 row_mask:0xf bank_mask:0x3
	v_add_f32_dpp v137, v137, v137 row_ror:8 row_mask:0xf bank_mask:0x3
	v_add_f32_dpp v138, v138, v138 row_ror:8 row_mask:0xf bank_mask:0x3
	v_add_f32_dpp v139, v139, v139 row_ror:8 row_mask:0xf bank_mask:0x3
	v_add_f32_dpp v132, v140, v140 row_ror:8 row_mask:0xf bank_mask:0xc
	v_add_f32_dpp v133, v141, v141 row_ror:8 row_mask:0xf bank_mask:0xc
	v_add_f32_dpp v134, v142, v142 row_ror:8 row_mask:0xf bank_mask:0xc
	v_add_f32_dpp v135, v143, v143 row_ror:8 row_mask:0xf bank_mask:0xc
	v_add_f32_dpp v136, v144, v144 row_ror:8 row_mask:0xf bank_mask:0xc
	v_add_f32_dpp v137, v145, v145 row_ror:8 row_mask:0xf bank_mask:0xc
	v_add_f32_dpp v138, v146, v146 row_ror:8 row_mask:0xf bank_mask:0xc
	v_add_f32_dpp v139, v147, v147 row_ror:8 row_mask:0xf bank_mask:0xc
	v_add_f32_dpp v132, v132, v132 row_ror:12 row_mask:0xf bank_mask:0x5
	v_add_f32_dpp v133, v133, v133 row_ror:12 row_mask:0xf bank_mask:0x5
	v_add_f32_dpp v134, v134, v134 row_ror:12 row_mask:0xf bank_mask:0x5
	v_add_f32_dpp v135, v135, v135 row_ror:12 row_mask:0xf bank_mask:0x5
	v_add_f32_dpp v132, v136, v136 row_ror:4 row_mask:0xf bank_mask:0xa
	v_add_f32_dpp v133, v137, v137 row_ror:4 row_mask:0xf bank_mask:0xa
	v_add_f32_dpp v134, v138, v138 row_ror:4 row_mask:0xf bank_mask:0xa
	v_add_f32_dpp v135, v139, v139 row_ror:4 row_mask:0xf bank_mask:0xa
	v_add_f32_dpp v140, v132, v132 quad_perm:[2,3,0,1] row_mask:0xf bank_mask:0xf
	v_add_f32_dpp v142, v134, v134 quad_perm:[2,3,0,1] row_mask:0xf bank_mask:0xf
	v_add_f32_dpp v141, v133, v133 quad_perm:[2,3,0,1] row_mask:0xf bank_mask:0xf
	v_add_f32_dpp v143, v135, v135 quad_perm:[2,3,0,1] row_mask:0xf bank_mask:0xf
	v_cndmask_b32_e64 v132, v140, v142, s[76:77]
	v_cndmask_b32_e64 v133, v141, v143, s[76:77]
	s_nop 0
	v_add_f32_dpp v196, v132, v132 quad_perm:[1,0,3,2] row_mask:0xf bank_mask:0xf
	v_add_f32_dpp v197, v133, v133 quad_perm:[1,0,3,2] row_mask:0xf bank_mask:0xf
	v_cndmask_b32_e64 v177, v196, v197, s[78:79]
	s_nop 1
	v_permlane16_swap_b32_e32 v176, v177
	v_add_f32_e32 v178, v176, v177
	v_mul_f32_e32 v178, 0x3e0293ee, v178
	v_add_f32_e32 v178, v178, v192
	v_exp_f32_e64 v198, -v178
	s_nop 0
	v_add_f32_e32 v198, 1.0, v198
	v_rcp_f32_e32 v179, v198
	s_nop 0
	v_sub_f32_e32 v180, 1.0, v179
	v_mov_b32_e32 v181, v180
	s_nop 1
	v_permlane32_swap_b32_e32 v180, v181
	v_mul_f32_e32 v183, v180, v181
	s_nop 1
	v_mul_f32_dpp v183, v183, v183 row_shl:1 row_mask:0xf bank_mask:0xf
	s_nop 1
	v_mul_f32_dpp v183, v183, v183 row_shl:2 row_mask:0xf bank_mask:0xf
	s_nop 1
	v_mul_f32_dpp v183, v183, v183 row_shl:4 row_mask:0xf bank_mask:0xf
	s_nop 1
	v_mul_f32_dpp v183, v183, v183 row_shl:8 row_mask:0xf bank_mask:0xf
	s_nop 0
	v_readlane_b32 s33, v183, 16
	v_mov_b32_e32 v184, 1.0
	s_nop 0
	v_mov_b32_e32 v185, s33
	s_nop 1
	v_mul_f32_dpp v183, v183, v185 quad_perm:[0,1,2,3] row_mask:0x5 bank_mask:0xf
	v_mov_b32_dpp v184, v185 quad_perm:[0,1,2,3] row_mask:0x5 bank_mask:0xf
	s_nop 1
	v_mov_b32_dpp v184, v183 row_shl:1 row_mask:0xf bank_mask:0xf
	v_mul_f32_e32 v186, v179, v184
	s_nop 1
	v_mul_f32_dpp v186, v186, v181 quad_perm:[0,1,2,3] row_mask:0x3 bank_mask:0xf
	s_cmp_eq_u32 s31, 0
	s_cbranch_scc1 .Ldqa_tail
	s_waitcnt lgkmcnt(0)
	s_mov_b32 s12, s29
	s_mov_b32 s13, 0
	s_lshl_b64 s[12:13], s[12:13], 19
	s_and_b32 s14, s8, 1
	s_lshl_b32 s14, s14, 18
	s_lshl_b32 s15, s7, 9
	s_or_b32 s14, s14, s15
	s_or_b32 s80, s12, s14
	s_mov_b32 s81, s13
	s_add_u32 s64, s50, s80
	s_addc_u32 s65, s51, s81
	s_mul_i32 s16, s6, 0x7040
	s_add_u32 s16, s16, s15
	s_add_u32 s16, s60, s16
	s_addc_u32 s17, s61, 0
	global_load_dwordx4 v[156:159], v193, s[16:17]
	s_barrier
; __device__ __forceinline__ void sb_decode_stream(Frame& F, unsigned* qctr, int base, int limit) {
;     ...
;         f32x4 o4 = {0.f, 0.f, 0.f, 0.f};
; #pragma unroll
;         for (int i = 0; i < 16; ++i) { const float aj = __shfl(a, 2 * i + half); o4 += aj * A[i]; }
;         const f32x4 q4n = *(const f32x4*)(SSP(S_PROJ) + (size_t)bn * IN_COLS + hn * HD + 4 * l32);
; #pragma unroll
;         for (int i = 0; i < 16; ++i) A[i] = __builtin_nontemporal_load((const f32x4*)(CK + cbn + (size_t)(2 * i) * stepn));
; #pragma unroll
;         for (int i = 0; i < 16; ++i) { const float aj = __shfl(a, 32 + 2 * i + half); o4 += aj * B[i]; }
; #pragma unroll
;         for (int i = 0; i < 16; ++i) B[i] = __builtin_nontemporal_load((const f32x4*)(CK + cbn + (size_t)(32 + 2 * i) * stepn));
	v_mov_b32_e32 v160, 0
	v_mov_b32_e32 v161, 0
	v_mov_b32_e32 v162, 0
	v_mov_b32_e32 v163, 0
	v_mov_b32_e32 v164, 0
	v_mov_b32_e32 v165, 0
	v_mov_b32_e32 v166, 0
	v_mov_b32_e32 v167, 0
	ds_bpermute_b32 v168, v188, v186 offset:0
	ds_bpermute_b32 v170, v188, v186 offset:4
	ds_bpermute_b32 v172, v188, v186 offset:8
	ds_bpermute_b32 v174, v188, v186 offset:12
	s_waitcnt vmcnt(32) lgkmcnt(3)
	v_pk_fma_f32 v[160:161], v[4:5], v[168:169], v[160:161] op_sel_hi:[1,0,1]
	v_pk_fma_f32 v[162:163], v[6:7], v[168:169], v[162:163] op_sel_hi:[1,0,1]
	global_load_dwordx4 v[4:7], v187, s[64:65] sc1 nt
	s_add_u32 s64, s64, 0x2000
	s_addc_u32 s65, s65, 0
	ds_bpermute_b32 v168, v188, v186 offset:16
	s_waitcnt vmcnt(32) lgkmcnt(3)
	v_pk_fma_f32 v[164:165], v[8:9], v[170:171], v[164:165] op_sel_hi:[1,0,1]
	v_pk_fma_f32 v[166:167], v[10:11], v[170:171], v[166:167] op_sel_hi:[1,0,1]
	global_load_dwordx4 v[8:11], v187, s[64:65] sc1 nt
	s_add_u32 s64, s64, 0x2000
	s_addc_u32 s65, s65, 0
	ds_bpermute_b32 v170, v188, v186 offset:20
	s_waitcnt vmcnt(32) lgkmcnt(3)
	v_pk_fma_f32 v[160:161], v[12:13], v[172:173], v[160:161] op_sel_hi:[1,0,1]
	v_pk_fma_f32 v[162:163], v[14:15], v[172:173], v[162:163] op_sel_hi:[1,0,1]
	global_load_dwordx4 v[12:15], v187, s[64:65] sc1 nt
	s_add_u32 s64, s64, 0x2000
	s_addc_u32 s65, s65, 0
	ds_bpermute_b32 v172, v188, v186 offset:24
	s_waitcnt vmcnt(32) lgkmcnt(3)
	v_pk_fma_f32 v[164:165], v[16:17], v[174:175], v[164:165] op_sel_hi:[1,0,1]
	v_pk_fma_f32 v[166:167], v[18:19], v[174:175], v[166:167] op_sel_hi:[1,0,1]
	global_load_dwordx4 v[16:19], v187, s[64:65] sc1 nt
	s_add_u32 s64, s64, 0x2000
	s_addc_u32 s65, s65, 0
	ds_bpermute_b32 v174, v188, v186 offset:28
	s_waitcnt vmcnt(32) lgkmcnt(3)
	v_pk_fma_f32 v[160:161], v[20:21], v[168:169], v[160:161] op_sel_hi:[1,0,1]
	v_pk_fma_f32 v[162:163], v[22:23], v[168:169], v[162:163] op_sel_hi:[1,0,1]
	global_load_dwordx4 v[20:23], v187, s[64:65] sc1 nt
	s_add_u32 s64, s64, 0x2000
	s_addc_u32 s65, s65, 0
	ds_bpermute_b32 v168, v188, v186 offset:32
	s_waitcnt vmcnt(32) lgkmcnt(3)
	v_pk_fma_f32 v[164:165], v[24:25], v[170:171], v[164:165] op_sel_hi:[1,0,1]
	v_pk_fma_f32 v[166:167], v[26:27], v[170:171], v[166:167] op_sel_hi:[1,0,1]
	global_load_dwordx4 v[24:27], v187, s[64:65] sc1 nt
	s_add_u32 s64, s64, 0x2000
	s_addc_u32 s65, s65, 0
	ds_bpermute_b32 v170, v188, v186 offset:36
	s_waitcnt vmcnt(32) lgkmcnt(3)
	v_pk_fma_f32 v[160:161], v[28:29], v[172:173], v[160:161] op_sel_hi:[1,0,1]
	v_pk_fma_f32 v[162:163], v[30:31], v[172:173], v[162:163] op_sel_hi:[1,0,1]
	global_load_dwordx4 v[28:31], v187, s[64:65] sc1 nt
	s_add_u32 s64, s64, 0x2000
	s_addc_u32 s65, s65, 0
	ds_bpermute_b32 v172, v188, v186 offset:40
	s_waitcnt vmcnt(32) lgkmcnt(3)
	v_pk_fma_f32 v[164:165], v[32:33], v[174:175], v[164:165] op_sel_hi:[1,0,1]
	v_pk_fma_f32 v[166:167], v[34:35], v[174:175], v[166:167] op_sel_hi:[1,0,1]
	global_load_dwordx4 v[32:35], v187, s[64:65] sc1 nt
	s_add_u32 s64, s64, 0x2000
	s_addc_u32 s65, s65, 0
	ds_bpermute_b32 v174, v188, v186 offset:44
	s_waitcnt vmcnt(32) lgkmcnt(3)
	v_pk_fma_f32 v[160:161], v[36:37], v[168:169], v[160:161] op_sel_hi:[1,0,1]
	v_pk_fma_f32 v[162:163], v[38:39], v[168:169], v[162:163] op_sel_hi:[1,0,1]
	global_load_dwordx4 v[36:39], v187, s[64:65] sc1 nt
	s_add_u32 s64, s64, 0x2000
	s_addc_u32 s65, s65, 0
	ds_bpermute_b32 v168, v188, v186 offset:48
	s_waitcnt vmcnt(32) lgkmcnt(3)
	v_pk_fma_f32 v[164:165], v[40:41], v[170:171], v[164:165] op_sel_hi:[1,0,1]
	v_pk_fma_f32 v[166:167], v[42:43], v[170:171], v[166:167] op_sel_hi:[1,0,1]
	global_load_dwordx4 v[40:43], v187, s[64:65] sc1 nt
	s_add_u32 s64, s64, 0x2000
	s_addc_u32 s65, s65, 0
	ds_bpermute_b32 v170, v188, v186 offset:52
	s_waitcnt vmcnt(32) lgkmcnt(3)
	v_pk_fma_f32 v[160:161], v[44:45], v[172:173], v[160:161] op_sel_hi:[1,0,1]
	v_pk_fma_f32 v[162:163], v[46:47], v[172:173], v[162:163] op_sel_hi:[1,0,1]
	global_load_dwordx4 v[44:47], v187, s[64:65] sc1 nt
	s_add_u32 s64, s64, 0x2000
	s_addc_u32 s65, s65, 0
	ds_bpermute_b32 v172, v188, v186 offset:56
	s_waitcnt vmcnt(32) lgkmcnt(3)
	v_pk_fma_f32 v[164:165], v[48:49], v[174:175], v[164:165] op_sel_hi:[1,0,1]
	v_pk_fma_f32 v[166:167], v[50:51], v[174:175], v[166:167] op_sel_hi:[1,0,1]
	global_load_dwordx4 v[48:51], v187, s[64:65] sc1 nt
	s_add_u32 s64, s64, 0x2000
	s_addc_u32 s65, s65, 0
	ds_bpermute_b32 v174, v188, v186 offset:60
	s_waitcnt vmcnt(32) lgkmcnt(3)
	v_pk_fma_f32 v[160:161], v[52:53], v[168:169], v[160:161] op_sel_hi:[1,0,1]
	v_pk_fma_f32 v[162:163], v[54:55], v[168:169], v[162:163] op_sel_hi:[1,0,1]
	global_load_dwordx4 v[52:55], v187, s[64:65] sc1 nt
	s_add_u32 s64, s64, 0x2000
	s_addc_u32 s65, s65, 0
	ds_bpermute_b32 v168, v188, v186 offset:64
	s_waitcnt vmcnt(32) lgkmcnt(3)
	v_pk_fma_f32 v[164:165], v[56:57], v[170:171], v[164:165] op_sel_hi:[1,0,1]
	v_pk_fma_f32 v[166:167], v[58:59], v[170:171], v[166:167] op_sel_hi:[1,0,1]
	global_load_dwordx4 v[56:59], v187, s[64:65] sc1 nt
	s_add_u32 s64, s64, 0x2000
	s_addc_u32 s65, s65, 0
	ds_bpermute_b32 v170, v188, v186 offset:68
	s_waitcnt vmcnt(32) lgkmcnt(3)
	v_pk_fma_f32 v[160:161], v[60:61], v[172:173], v[160:161] op_sel_hi:[1,0,1]
	v_pk_fma_f32 v[162:163], v[62:63], v[172:173], v[162:163] op_sel_hi:[1,0,1]
	global_load_dwordx4 v[60:63], v187, s[64:65] sc1 nt
	s_add_u32 s64, s64, 0x2000
	s_addc_u32 s65, s65, 0
	ds_bpermute_b32 v172, v188, v186 offset:72
	s_waitcnt vmcnt(32) lgkmcnt(3)
	v_pk_fma_f32 v[164:165], v[64:65], v[174:175], v[164:165] op_sel_hi:[1,0,1]
	v_pk_fma_f32 v[166:167], v[66:67], v[174:175], v[166:167] op_sel_hi:[1,0,1]
	global_load_dwordx4 v[64:67], v187, s[64:65] sc1 nt
	s_add_u32 s64, s64, 0x2000
	s_addc_u32 s65, s65, 0
	s_barrier
; __device__ __forceinline__ void sb_decode_stream(Frame& F, unsigned* qctr, int base, int limit) {
;     ...
;         for (int i = 0; i < 16; ++i) { const float aj = __shfl(a, 32 + 2 * i + half); o4 += aj * B[i]; }
; #pragma unroll
;         for (int i = 0; i < 16; ++i) B[i] = __builtin_nontemporal_load((const f32x4*)(CK + cbn + (size_t)(32 + 2 * i) * stepn));
;         o4.x += __shfl_xor(o4.x, 32); o4.y += __shfl_xor(o4.y, 32); o4.z += __shfl_xor(o4.z, 32); o4.w += __shfl_xor(o4.w, 32);
;         float* P = SSP(S_PART) + ((size_t)bh * DSEG + blk) * DPART;
;         if (half == 0) *(f32x4*)(P + 4 * l32) = o4; if (lane == 0) P[128] = tot;
;         if (!more) break;
;         it = itn; cb = cbn; q4 = q4n;
	ds_bpermute_b32 v174, v188, v186 offset:76
	s_waitcnt vmcnt(32) lgkmcnt(3)
	v_pk_fma_f32 v[160:161], v[68:69], v[168:169], v[160:161] op_sel_hi:[1,0,1]
	v_pk_fma_f32 v[162:163], v[70:71], v[168:169], v[162:163] op_sel_hi:[1,0,1]
	global_load_dwordx4 v[68:71], v187, s[64:65] sc1 nt
	s_add_u32 s64, s64, 0x2000
	s_addc_u32 s65, s65, 0
	ds_bpermute_b32 v168, v188, v186 offset:80
	s_waitcnt vmcnt(32) lgkmcnt(3)
	v_pk_fma_f32 v[164:165], v[72:73], v[170:171], v[164:165] op_sel_hi:[1,0,1]
	v_pk_fma_f32 v[166:167], v[74:75], v[170:171], v[166:167] op_sel_hi:[1,0,1]
	global_load_dwordx4 v[72:75], v187, s[64:65] sc1 nt
	s_add_u32 s64, s64, 0x2000
	s_addc_u32 s65, s65, 0
	ds_bpermute_b32 v170, v188, v186 offset:84
	s_waitcnt vmcnt(32) lgkmcnt(3)
	v_pk_fma_f32 v[160:161], v[76:77], v[172:173], v[160:161] op_sel_hi:[1,0,1]
	v_pk_fma_f32 v[162:163], v[78:79], v[172:173], v[162:163] op_sel_hi:[1,0,1]
	global_load_dwordx4 v[76:79], v187, s[64:65] sc1 nt
	s_add_u32 s64, s64, 0x2000
	s_addc_u32 s65, s65, 0
	ds_bpermute_b32 v172, v188, v186 offset:88
	s_waitcnt vmcnt(32) lgkmcnt(3)
	v_pk_fma_f32 v[164:165], v[80:81], v[174:175], v[164:165] op_sel_hi:[1,0,1]
	v_pk_fma_f32 v[166:167], v[82:83], v[174:175], v[166:167] op_sel_hi:[1,0,1]
	global_load_dwordx4 v[80:83], v187, s[64:65] sc1 nt
	s_add_u32 s64, s64, 0x2000
	s_addc_u32 s65, s65, 0
	ds_bpermute_b32 v174, v188, v186 offset:92
	s_waitcnt vmcnt(32) lgkmcnt(3)
	v_pk_fma_f32 v[160:161], v[84:85], v[168:169], v[160:161] op_sel_hi:[1,0,1]
	v_pk_fma_f32 v[162:163], v[86:87], v[168:169], v[162:163] op_sel_hi:[1,0,1]
	global_load_dwordx4 v[84:87], v187, s[64:65] sc1 nt
	s_add_u32 s64, s64, 0x2000
	s_addc_u32 s65, s65, 0
	ds_bpermute_b32 v168, v188, v186 offset:96
	s_waitcnt vmcnt(32) lgkmcnt(3)
	v_pk_fma_f32 v[164:165], v[88:89], v[170:171], v[164:165] op_sel_hi:[1,0,1]
	v_pk_fma_f32 v[166:167], v[90:91], v[170:171], v[166:167] op_sel_hi:[1,0,1]
	global_load_dwordx4 v[88:91], v187, s[64:65] sc1 nt
	s_add_u32 s64, s64, 0x2000
	s_addc_u32 s65, s65, 0
	ds_bpermute_b32 v170, v188, v186 offset:100
	s_waitcnt vmcnt(32) lgkmcnt(3)
	v_pk_fma_f32 v[160:161], v[92:93], v[172:173], v[160:161] op_sel_hi:[1,0,1]
	v_pk_fma_f32 v[162:163], v[94:95], v[172:173], v[162:163] op_sel_hi:[1,0,1]
	global_load_dwordx4 v[92:95], v187, s[64:65] sc1 nt
	s_add_u32 s64, s64, 0x2000
	s_addc_u32 s65, s65, 0
	ds_bpermute_b32 v172, v188, v186 offset:104
	s_waitcnt vmcnt(32) lgkmcnt(3)
	v_pk_fma_f32 v[164:165], v[96:97], v[174:175], v[164:165] op_sel_hi:[1,0,1]
	v_pk_fma_f32 v[166:167], v[98:99], v[174:175], v[166:167] op_sel_hi:[1,0,1]
	global_load_dwordx4 v[96:99], v187, s[64:65] sc1 nt
	s_add_u32 s64, s64, 0x2000
	s_addc_u32 s65, s65, 0
	ds_bpermute_b32 v174, v188, v186 offset:108
	s_waitcnt vmcnt(32) lgkmcnt(3)
	v_pk_fma_f32 v[160:161], v[100:101], v[168:169], v[160:161] op_sel_hi:[1,0,1]
	v_pk_fma_f32 v[162:163], v[102:103], v[168:169], v[162:163] op_sel_hi:[1,0,1]
	global_load_dwordx4 v[100:103], v187, s[64:65] sc1 nt
	s_add_u32 s64, s64, 0x2000
	s_addc_u32 s65, s65, 0
	ds_bpermute_b32 v168, v188, v186 offset:112
	s_waitcnt vmcnt(32) lgkmcnt(3)
	v_pk_fma_f32 v[164:165], v[104:105], v[170:171], v[164:165] op_sel_hi:[1,0,1]
	v_pk_fma_f32 v[166:167], v[106:107], v[170:171], v[166:167] op_sel_hi:[1,0,1]
	global_load_dwordx4 v[104:107], v187, s[64:65] sc1 nt
	s_add_u32 s64, s64, 0x2000
	s_addc_u32 s65, s65, 0
	ds_bpermute_b32 v170, v188, v186 offset:116
	s_waitcnt vmcnt(32) lgkmcnt(3)
	v_pk_fma_f32 v[160:161], v[108:109], v[172:173], v[160:161] op_sel_hi:[1,0,1]
	v_pk_fma_f32 v[162:163], v[110:111], v[172:173], v[162:163] op_sel_hi:[1,0,1]
	global_load_dwordx4 v[108:111], v187, s[64:65] sc1 nt
	s_add_u32 s64, s64, 0x2000
	s_addc_u32 s65, s65, 0
	ds_bpermute_b32 v172, v188, v186 offset:120
	s_waitcnt vmcnt(32) lgkmcnt(3)
	v_pk_fma_f32 v[164:165], v[112:113], v[174:175], v[164:165] op_sel_hi:[1,0,1]
	v_pk_fma_f32 v[166:167], v[114:115], v[174:175], v[166:167] op_sel_hi:[1,0,1]
	global_load_dwordx4 v[112:115], v187, s[64:65] sc1 nt
	s_add_u32 s64, s64, 0x2000
	s_addc_u32 s65, s65, 0
	ds_bpermute_b32 v174, v188, v186 offset:124
	s_waitcnt vmcnt(32) lgkmcnt(3)
	v_pk_fma_f32 v[160:161], v[116:117], v[168:169], v[160:161] op_sel_hi:[1,0,1]
	v_pk_fma_f32 v[162:163], v[118:119], v[168:169], v[162:163] op_sel_hi:[1,0,1]
	global_load_dwordx4 v[116:119], v187, s[64:65] sc1 nt
	s_add_u32 s64, s64, 0x2000
	s_addc_u32 s65, s65, 0
	s_waitcnt vmcnt(32) lgkmcnt(2)
	v_pk_fma_f32 v[164:165], v[120:121], v[170:171], v[164:165] op_sel_hi:[1,0,1]
	v_pk_fma_f32 v[166:167], v[122:123], v[170:171], v[166:167] op_sel_hi:[1,0,1]
	global_load_dwordx4 v[120:123], v187, s[64:65] sc1 nt
	s_add_u32 s64, s64, 0x2000
	s_addc_u32 s65, s65, 0
	s_waitcnt vmcnt(32) lgkmcnt(1)
	v_pk_fma_f32 v[160:161], v[124:125], v[172:173], v[160:161] op_sel_hi:[1,0,1]
	v_pk_fma_f32 v[162:163], v[126:127], v[172:173], v[162:163] op_sel_hi:[1,0,1]
	global_load_dwordx4 v[124:127], v187, s[64:65] sc1 nt
	s_add_u32 s64, s64, 0x2000
	s_addc_u32 s65, s65, 0
	s_waitcnt vmcnt(32) lgkmcnt(0)
	v_pk_fma_f32 v[164:165], v[128:129], v[174:175], v[164:165] op_sel_hi:[1,0,1]
	v_pk_fma_f32 v[166:167], v[130:131], v[174:175], v[166:167] op_sel_hi:[1,0,1]
	global_load_dwordx4 v[128:131], v187, s[64:65] sc1 nt
	s_add_u32 s64, s64, 0x2000
	s_addc_u32 s65, s65, 0
	s_nop 1
	v_pk_add_f32 v[160:161], v[160:161], v[164:165]
	v_pk_add_f32 v[162:163], v[162:163], v[166:167]
	s_nop 1
	v_mov_b32_e32 v164, v160
	v_mov_b32_e32 v165, v161
	v_mov_b32_e32 v166, v162
	v_mov_b32_e32 v167, v163
	v_permlane32_swap_b32_e32 v160, v164
	v_permlane32_swap_b32_e32 v161, v165
	v_permlane32_swap_b32_e32 v162, v166
	v_permlane32_swap_b32_e32 v163, v167
	v_pk_add_f32 v[160:161], v[160:161], v[164:165]
	v_pk_add_f32 v[162:163], v[162:163], v[166:167]
	s_nop 1
	s_mov_b32 exec_hi, 0
	global_store_dwordx4 v193, v[160:163], s[70:71]
	s_mov_b32 exec_lo, 1
	global_store_dword v189, v183, s[70:71] offset:512
	s_mov_b64 exec, -1
	s_mov_b32 s72, s73
	s_branch .Ldqa_loop

; __device__ __forceinline__ void sb_decode_stream(Frame& F, unsigned* qctr, int base, int limit) {
;     ...
;     { const unsigned v = __hip_atomic_fetch_add(qctr, 1u, __ATOMIC_RELAXED, __HIP_MEMORY_SCOPE_AGENT);
;       it = (int)(__builtin_amdgcn_readfirstlane(v) >> 6); if (it >= limit) return; it += base; }
;     f32x4 A[16], B[16], q4;
;     size_t cb;
;     { const int b = it >> 11, h = it & 7, p0 = ((it >> 3) & 255) * 64;
;       const int page = PT[b * NPAGES + (p0 >> 7)];
;       cb = (((size_t)page * PAGE + (p0 & 127)) * NH + h) * HD + lo;
;       q4 = *(const f32x4*)(SSP(S_PROJ) + (size_t)b * IN_COLS + h * HD + 4 * l32);
; #pragma unroll
;       for (int i = 0; i < 16; ++i) A[i] = __builtin_nontemporal_load((const f32x4*)(CK + cb + (size_t)(2 * i) * (NH * HD)));
; #pragma unroll
;       for (int i = 0; i < 16; ++i) B[i] = __builtin_nontemporal_load((const f32x4*)(CK + cb + (size_t)(32 + 2 * i) * (NH * HD))); }
.Ldqc_sh1:
	s_barrier
	ds_read_b32 v201, v200
	s_xor_b32 s37, s37, 4
	s_waitcnt lgkmcnt(0)
	v_readfirstlane_b32 s2, v201
	s_nop 0
	s_lshr_b32 s72, s2, 6
	s_cmp_ge_u32 s72, 0x2800
	s_cbranch_scc1 .Ldqc_exit
	s_add_u32 s72, s72, s94
	s_min_u32 s72, s72, 0x27ff
	s_mov_b32 s74, s72
	s_mov_b32 s75, 0
	s_add_u32 s72, s72, 0x1800
	s_waitcnt lgkmcnt(0)
	s_lshr_b32 s6, s72, 11
	s_and_b32 s7, s72, 7
	s_bfe_u32 s8, s72, 0x80003
	s_lshl_b32 s9, s6, 7
	s_lshr_b32 s10, s8, 1
	s_or_b32 s9, s9, s10
	s_lshl_b32 s9, s9, 2
	s_lshl_b32 s10, s7, 2
	s_load_dword s29, s[54:55], s9
	s_load_dword s30, s[56:57], s10
	s_waitcnt lgkmcnt(0)
	s_mov_b32 s12, s29
	s_mov_b32 s13, 0
	s_lshl_b64 s[12:13], s[12:13], 19
	s_and_b32 s14, s8, 1
	s_lshl_b32 s14, s14, 18
	s_lshl_b32 s15, s7, 9
	s_or_b32 s14, s14, s15
	s_or_b32 s80, s12, s14
	s_mov_b32 s81, s13
	s_add_u32 s64, s50, s80
	s_addc_u32 s65, s51, s81
	s_mul_i32 s16, s6, 0x7040
	s_add_u32 s16, s16, s15
	s_add_u32 s16, s60, s16
	s_addc_u32 s17, s61, 0
	global_load_dwordx4 v[156:159], v193, s[16:17]
	global_load_dwordx4 v[4:7], v187, s[64:65] sc1 nt
	s_add_u32 s64, s64, 0x2000
	s_addc_u32 s65, s65, 0
	global_load_dwordx4 v[8:11], v187, s[64:65] sc1 nt
	s_add_u32 s64, s64, 0x2000
	s_addc_u32 s65, s65, 0
	global_load_dwordx4 v[12:15], v187, s[64:65] sc1 nt
	s_add_u32 s64, s64, 0x2000
	s_addc_u32 s65, s65, 0
	global_load_dwordx4 v[16:19], v187, s[64:65] sc1 nt
	s_add_u32 s64, s64, 0x2000
	s_addc_u32 s65, s65, 0
	global_load_dwordx4 v[20:23], v187, s[64:65] sc1 nt
	s_add_u32 s64, s64, 0x2000
	s_addc_u32 s65, s65, 0
	global_load_dwordx4 v[24:27], v187, s[64:65] sc1 nt
	s_add_u32 s64, s64, 0x2000
	s_addc_u32 s65, s65, 0
	global_load_dwordx4 v[28:31], v187, s[64:65] sc1 nt
	s_add_u32 s64, s64, 0x2000
	s_addc_u32 s65, s65, 0
	global_load_dwordx4 v[32:35], v187, s[64:65] sc1 nt
	s_add_u32 s64, s64, 0x2000
	s_addc_u32 s65, s65, 0
	global_load_dwordx4 v[36:39], v187, s[64:65] sc1 nt
	s_add_u32 s64, s64, 0x2000
	s_addc_u32 s65, s65, 0
	global_load_dwordx4 v[40:43], v187, s[64:65] sc1 nt
	s_add_u32 s64, s64, 0x2000
	s_addc_u32 s65, s65, 0
	global_load_dwordx4 v[44:47], v187, s[64:65] sc1 nt
	s_add_u32 s64, s64, 0x2000
	s_addc_u32 s65, s65, 0
	global_load_dwordx4 v[48:51], v187, s[64:65] sc1 nt
	s_add_u32 s64, s64, 0x2000
	s_addc_u32 s65, s65, 0
	global_load_dwordx4 v[52:55], v187, s[64:65] sc1 nt
	s_add_u32 s64, s64, 0x2000
	s_addc_u32 s65, s65, 0
	global_load_dwordx4 v[56:59], v187, s[64:65] sc1 nt
	s_add_u32 s64, s64, 0x2000
	s_addc_u32 s65, s65, 0
	global_load_dwordx4 v[60:63], v187, s[64:65] sc1 nt
	s_add_u32 s64, s64, 0x2000
	s_addc_u32 s65, s65, 0
	global_load_dwordx4 v[64:67], v187, s[64:65] sc1 nt
	s_add_u32 s64, s64, 0x2000
	s_addc_u32 s65, s65, 0
	global_load_dwordx4 v[68:71], v187, s[64:65] sc1 nt
	s_add_u32 s64, s64, 0x2000
	s_addc_u32 s65, s65, 0
	global_load_dwordx4 v[72:75], v187, s[64:65] sc1 nt
	s_add_u32 s64, s64, 0x2000
	s_addc_u32 s65, s65, 0
	global_load_dwordx4 v[76:79], v187, s[64:65] sc1 nt
	s_add_u32 s64, s64, 0x2000
	s_addc_u32 s65, s65, 0
	global_load_dwordx4 v[80:83], v187, s[64:65] sc1 nt
	s_add_u32 s64, s64, 0x2000
	s_addc_u32 s65, s65, 0
	global_load_dwordx4 v[84:87], v187, s[64:65] sc1 nt
	s_add_u32 s64, s64, 0x2000
	s_addc_u32 s65, s65, 0
	global_load_dwordx4 v[88:91], v187, s[64:65] sc1 nt
	s_add_u32 s64, s64, 0x2000
	s_addc_u32 s65, s65, 0
	global_load_dwordx4 v[92:95], v187, s[64:65] sc1 nt
	s_add_u32 s64, s64, 0x2000
	s_addc_u32 s65, s65, 0
	global_load_dwordx4 v[96:99], v187, s[64:65] sc1 nt
	s_add_u32 s64, s64, 0x2000
	s_addc_u32 s65, s65, 0
	global_load_dwordx4 v[100:103], v187, s[64:65] sc1 nt
	s_add_u32 s64, s64, 0x2000
	s_addc_u32 s65, s65, 0
	global_load_dwordx4 v[104:107], v187, s[64:65] sc1 nt
	s_add_u32 s64, s64, 0x2000
	s_addc_u32 s65, s65, 0
	global_load_dwordx4 v[108:111], v187, s[64:65] sc1 nt
	s_add_u32 s64, s64, 0x2000
	s_addc_u32 s65, s65, 0
	global_load_dwordx4 v[112:115], v187, s[64:65] sc1 nt
	s_add_u32 s64, s64, 0x2000
	s_addc_u32 s65, s65, 0
	global_load_dwordx4 v[116:119], v187, s[64:65] sc1 nt
	s_add_u32 s64, s64, 0x2000
	s_addc_u32 s65, s65, 0
	global_load_dwordx4 v[120:123], v187, s[64:65] sc1 nt
	s_add_u32 s64, s64, 0x2000
	s_addc_u32 s65, s65, 0
	global_load_dwordx4 v[124:127], v187, s[64:65] sc1 nt
	s_add_u32 s64, s64, 0x2000
	s_addc_u32 s65, s65, 0
	global_load_dwordx4 v[128:131], v187, s[64:65] sc1 nt
	s_add_u32 s64, s64, 0x2000
	s_addc_u32 s65, s65, 0
	global_load_dword v194, v189, s[58:59]
	global_load_dword v195, v189, s[58:59]

; __device__ __forceinline__ void sb_decode_stream(Frame& F, unsigned* qctr, int base, int limit) {
;     ...
;         const int bh = ((it >> 11) << 3) | (it & 7), blk = (it >> 3) & 255, h = it & 7;
;         const unsigned vn = __hip_atomic_fetch_add(qctr, 1u, __ATOMIC_RELAXED, __HIP_MEMORY_SCOPE_AGENT);
;         const float k2 = kin(12)[h] * 1.4426950408889634f;
;         int zi = 0;
;     ...
;         DEC_SCORES(A, 0);
; #pragma unroll
;         for (int i = 0; i < 16; ++i) A[i] = __builtin_nontemporal_load((const f32x4*)(CV + cb + (size_t)(2 * i) * (NH * HD)));
;         DEC_SCORES(B, 1);
;     ...
; #pragma unroll
;         for (int i = 0; i < 16; ++i) B[i] = __builtin_nontemporal_load((const f32x4*)(CV + cb + (size_t)(32 + 2 * i) * (NH * HD)));
;         const float z = __builtin_bit_cast(float, zi);
;         const float e = __builtin_amdgcn_exp2f(-(z * k1 + k2));
;         const float be = __builtin_amdgcn_rcpf(1.0f + e), m = 1.0f - be;
;         float s = m;
; #pragma unroll
;         for (int o = 1; o < 64; o <<= 1) { const float t = __shfl_down(s, o); if (lane + o < 64) s *= t; }
;         const float tot = __shfl(s, 0);
;         const float sx = __shfl_down(s, 1);
;         const float a = be * (lane < 63 ? sx : 1.0f);
;         int itn = (int)(__builtin_amdgcn_readfirstlane(vn) >> 6); const bool more = itn < limit; itn = more ? itn + base : it;
;         const int bn = itn >> 11, hn = itn & 7, p0n = ((itn >> 3) & 255) * 64;
;         const int pagen = PT[bn * NPAGES + (p0n >> 7)];
;         const size_t cbn = (((size_t)pagen * PAGE + (p0n & 127)) * NH + hn) * HD + lo;
;         const size_t stepn = more ? (size_t)(NH * HD) : 0;
.Ldqc_sh2:
	s_barrier
	ds_read_b32 v201, v200
	s_xor_b32 s37, s37, 4
	s_waitcnt lgkmcnt(0)
	v_readfirstlane_b32 s2, v201
	s_nop 0
	s_lshr_b32 s73, s2, 6
	s_cmp_lt_u32 s73, 0x2800
	s_cselect_b32 s31, 1, 0
	s_add_u32 s73, s73, s94
	s_min_u32 s73, s73, 0x27ff
	s_add_u32 s73, s73, 0x1800
	s_cmp_eq_u32 s31, 1
	s_cselect_b32 s73, s73, s72
	s_lshr_b32 s6, s73, 11
	s_and_b32 s7, s73, 7
	s_bfe_u32 s8, s73, 0x80003
	s_lshl_b32 s9, s6, 7
	s_lshr_b32 s10, s8, 1
	s_or_b32 s9, s9, s10
	s_lshl_b32 s9, s9, 2
	s_lshl_b32 s10, s7, 2
	s_load_dword s29, s[54:55], s9
	s_load_dword s30, s[56:57], s10
	v_add_f32_dpp v132, v132, v132 row_ror:8 row_mask:0xf bank_mask:0x3
	v_add_f32_dpp v133, v133, v133 row_ror:8 row_mask:0xf bank_mask:0x3
	v_add_f32_dpp v134, v134, v134 row_ror:8 row_mask:0xf bank_mask:0x3
	v_add_f32_dpp v135, v135, v135 row_ror:8 row_mask:0xf bank_mask:0x3
	v_add_f32_dpp v136, v136, v136 row_ror:8 row_mask:0xf bank_mask:0x3
	v_add_f32_dpp v137, v137, v137 row_ror:8 row_mask:0xf bank_mask:0x3
	v_add_f32_dpp v138, v138, v138 row_ror:8 row_mask:0xf bank_mask:0x3
	v_add_f32_dpp v139, v139, v139 row_ror:8 row_mask:0xf bank_mask:0x3
	v_add_f32_dpp v132, v140, v140 row_ror:8 row_mask:0xf bank_mask:0xc
	v_add_f32_dpp v133, v141, v141 row_ror:8 row_mask:0xf bank_mask:0xc
	v_add_f32_dpp v134, v142, v142 row_ror:8 row_mask:0xf bank_mask:0xc
	v_add_f32_dpp v135, v143, v143 row_ror:8 row_mask:0xf bank_mask:0xc
	v_add_f32_dpp v136, v144, v144 row_ror:8 row_mask:0xf bank_mask:0xc
	v_add_f32_dpp v137, v145, v145 row_ror:8 row_mask:0xf bank_mask:0xc
	v_add_f32_dpp v138, v146, v146 row_ror:8 row_mask:0xf bank_mask:0xc
	v_add_f32_dpp v139, v147, v147 row_ror:8 row_mask:0xf bank_mask:0xc
	v_add_f32_dpp v132, v132, v132 row_ror:12 row_mask:0xf bank_mask:0x5
	v_add_f32_dpp v133, v133, v133 row_ror:12 row_mask:0xf bank_mask:0x5
	v_add_f32_dpp v134, v134, v134 row_ror:12 row_mask:0xf bank_mask:0x5
	v_add_f32_dpp v135, v135, v135 row_ror:12 row_mask:0xf bank_mask:0x5
	v_add_f32_dpp v132, v136, v136 row_ror:4 row_mask:0xf bank_mask:0xa
	v_add_f32_dpp v133, v137, v137 row_ror:4 row_mask:0xf bank_mask:0xa
	v_add_f32_dpp v134, v138, v138 row_ror:4 row_mask:0xf bank_mask:0xa
	v_add_f32_dpp v135, v139, v139 row_ror:4 row_mask:0xf bank_mask:0xa
	v_add_f32_dpp v140, v132, v132 quad_perm:[2,3,0,1] row_mask:0xf bank_mask:0xf
	v_add_f32_dpp v142, v134, v134 quad_perm:[2,3,0,1] row_mask:0xf bank_mask:0xf
	v_add_f32_dpp v141, v133, v133 quad_perm:[2,3,0,1] row_mask:0xf bank_mask:0xf
	v_add_f32_dpp v143, v135, v135 quad_perm:[2,3,0,1] row_mask:0xf bank_mask:0xf
	v_cndmask_b32_e64 v132, v140, v142, s[76:77]
	v_cndmask_b32_e64 v133, v141, v143, s[76:77]
	s_nop 0
	v_add_f32_dpp v196, v132, v132 quad_perm:[1,0,3,2] row_mask:0xf bank_mask:0xf
	v_add_f32_dpp v197, v133, v133 quad_perm:[1,0,3,2] row_mask:0xf bank_mask:0xf
	v_cndmask_b32_e64 v177, v196, v197, s[78:79]
	s_nop 1
	v_permlane16_swap_b32_e32 v176, v177
	v_add_f32_e32 v178, v176, v177
	v_mul_f32_e32 v178, 0x3e0293ee, v178
	v_add_f32_e32 v178, v178, v192
	v_exp_f32_e64 v198, -v178
	s_nop 0
	v_add_f32_e32 v198, 1.0, v198
	v_rcp_f32_e32 v179, v198
	s_nop 0
	v_sub_f32_e32 v180, 1.0, v179
	v_mov_b32_e32 v181, v180
	s_nop 1
	v_permlane32_swap_b32_e32 v180, v181
	v_mul_f32_e32 v183, v180, v181
	s_nop 1
	v_mul_f32_dpp v183, v183, v183 row_shl:1 row_mask:0xf bank_mask:0xf
	s_nop 1
	v_mul_f32_dpp v183, v183, v183 row_shl:2 row_mask:0xf bank_mask:0xf
	s_nop 1
	v_mul_f32_dpp v183, v183, v183 row_shl:4 row_mask:0xf bank_mask:0xf
	s_nop 1
	v_mul_f32_dpp v183, v183, v183 row_shl:8 row_mask:0xf bank_mask:0xf
	s_nop 0
	v_readlane_b32 s33, v183, 16
	v_mov_b32_e32 v184, 1.0
	s_nop 0
	v_mov_b32_e32 v185, s33
	s_nop 1
	v_mul_f32_dpp v183, v183, v185 quad_perm:[0,1,2,3] row_mask:0x5 bank_mask:0xf
	v_mov_b32_dpp v184, v185 quad_perm:[0,1,2,3] row_mask:0x5 bank_mask:0xf
	s_nop 1
	v_mov_b32_dpp v184, v183 row_shl:1 row_mask:0xf bank_mask:0xf
	v_mul_f32_e32 v186, v179, v184
	s_nop 1
	v_mul_f32_dpp v186, v186, v181 quad_perm:[0,1,2,3] row_mask:0x3 bank_mask:0xf
	s_cmp_eq_u32 s31, 0
	s_cbranch_scc1 .Ldqc_tail
	s_waitcnt lgkmcnt(0)
	s_mov_b32 s12, s29
	s_mov_b32 s13, 0
	s_lshl_b64 s[12:13], s[12:13], 19
	s_and_b32 s14, s8, 1
	s_lshl_b32 s14, s14, 18
	s_lshl_b32 s15, s7, 9
	s_or_b32 s14, s14, s15
	s_or_b32 s80, s12, s14
	s_mov_b32 s81, s13
	s_add_u32 s64, s50, s80
	s_addc_u32 s65, s51, s81
	s_mul_i32 s16, s6, 0x7040
	s_add_u32 s16, s16, s15
	s_add_u32 s16, s60, s16
	s_addc_u32 s17, s61, 0
	global_load_dwordx4 v[156:159], v193, s[16:17]
	s_barrier
; __device__ __forceinline__ void sb_decode_stream(Frame& F, unsigned* qctr, int base, int limit) {
;     ...
;         f32x4 o4 = {0.f, 0.f, 0.f, 0.f};
; #pragma unroll
;         for (int i = 0; i < 16; ++i) { const float aj = __shfl(a, 2 * i + half); o4 += aj * A[i]; }
;         const f32x4 q4n = *(const f32x4*)(SSP(S_PROJ) + (size_t)bn * IN_COLS + hn * HD + 4 * l32);
; #pragma unroll
;         for (int i = 0; i < 16; ++i) A[i] = __builtin_nontemporal_load((const f32x4*)(CK + cbn + (size_t)(2 * i) * stepn));
; #pragma unroll
;         for (int i = 0; i < 16; ++i) { const float aj = __shfl(a, 32 + 2 * i + half); o4 += aj * B[i]; }
; #pragma unroll
;         for (int i = 0; i < 16; ++i) B[i] = __builtin_nontemporal_load((const f32x4*)(CK + cbn + (size_t)(32 + 2 * i) * stepn));
	v_mov_b32_e32 v160, 0
	v_mov_b32_e32 v161, 0
	v_mov_b32_e32 v162, 0
	v_mov_b32_e32 v163, 0
	v_mov_b32_e32 v164, 0
	v_mov_b32_e32 v165, 0
	v_mov_b32_e32 v166, 0
	v_mov_b32_e32 v167, 0
	ds_bpermute_b32 v168, v188, v186 offset:0
	ds_bpermute_b32 v170, v188, v186 offset:4
	ds_bpermute_b32 v172, v188, v186 offset:8
	ds_bpermute_b32 v174, v188, v186 offset:12
	s_waitcnt vmcnt(32) lgkmcnt(3)
	v_pk_fma_f32 v[160:161], v[4:5], v[168:169], v[160:161] op_sel_hi:[1,0,1]
	v_pk_fma_f32 v[162:163], v[6:7], v[168:169], v[162:163] op_sel_hi:[1,0,1]
	global_load_dwordx4 v[4:7], v187, s[64:65] sc1 nt
	s_add_u32 s64, s64, 0x2000
	s_addc_u32 s65, s65, 0
	ds_bpermute_b32 v168, v188, v186 offset:16
	s_waitcnt vmcnt(32) lgkmcnt(3)
	v_pk_fma_f32 v[164:165], v[8:9], v[170:171], v[164:165] op_sel_hi:[1,0,1]
	v_pk_fma_f32 v[166:167], v[10:11], v[170:171], v[166:167] op_sel_hi:[1,0,1]
	global_load_dwordx4 v[8:11], v187, s[64:65] sc1 nt
	s_add_u32 s64, s64, 0x2000
	s_addc_u32 s65, s65, 0
	ds_bpermute_b32 v170, v188, v186 offset:20
	s_waitcnt vmcnt(32) lgkmcnt(3)
	v_pk_fma_f32 v[160:161], v[12:13], v[172:173], v[160:161] op_sel_hi:[1,0,1]
	v_pk_fma_f32 v[162:163], v[14:15], v[172:173], v[162:163] op_sel_hi:[1,0,1]
	global_load_dwordx4 v[12:15], v187, s[64:65] sc1 nt
	s_add_u32 s64, s64, 0x2000
	s_addc_u32 s65, s65, 0
	ds_bpermute_b32 v172, v188, v186 offset:24
	s_waitcnt vmcnt(32) lgkmcnt(3)
	v_pk_fma_f32 v[164:165], v[16:17], v[174:175], v[164:165] op_sel_hi:[1,0,1]
	v_pk_fma_f32 v[166:167], v[18:19], v[174:175], v[166:167] op_sel_hi:[1,0,1]
	global_load_dwordx4 v[16:19], v187, s[64:65] sc1 nt
	s_add_u32 s64, s64, 0x2000
	s_addc_u32 s65, s65, 0
	ds_bpermute_b32 v174, v188, v186 offset:28
	s_waitcnt vmcnt(32) lgkmcnt(3)
	v_pk_fma_f32 v[160:161], v[20:21], v[168:169], v[160:161] op_sel_hi:[1,0,1]
	v_pk_fma_f32 v[162:163], v[22:23], v[168:169], v[162:163] op_sel_hi:[1,0,1]
	global_load_dwordx4 v[20:23], v187, s[64:65] sc1 nt
	s_add_u32 s64, s64, 0x2000
	s_addc_u32 s65, s65, 0
	ds_bpermute_b32 v168, v188, v186 offset:32
	s_waitcnt vmcnt(32) lgkmcnt(3)
	v_pk_fma_f32 v[164:165], v[24:25], v[170:171], v[164:165] op_sel_hi:[1,0,1]
	v_pk_fma_f32 v[166:167], v[26:27], v[170:171], v[166:167] op_sel_hi:[1,0,1]
	global_load_dwordx4 v[24:27], v187, s[64:65] sc1 nt
	s_add_u32 s64, s64, 0x2000
	s_addc_u32 s65, s65, 0
	ds_bpermute_b32 v170, v188, v186 offset:36
	s_waitcnt vmcnt(32) lgkmcnt(3)
	v_pk_fma_f32 v[160:161], v[28:29], v[172:173], v[160:161] op_sel_hi:[1,0,1]
	v_pk_fma_f32 v[162:163], v[30:31], v[172:173], v[162:163] op_sel_hi:[1,0,1]
	global_load_dwordx4 v[28:31], v187, s[64:65] sc1 nt
	s_add_u32 s64, s64, 0x2000
	s_addc_u32 s65, s65, 0
	ds_bpermute_b32 v172, v188, v186 offset:40
	s_waitcnt vmcnt(32) lgkmcnt(3)
	v_pk_fma_f32 v[164:165], v[32:33], v[174:175], v[164:165] op_sel_hi:[1,0,1]
	v_pk_fma_f32 v[166:167], v[34:35], v[174:175], v[166:167] op_sel_hi:[1,0,1]
	global_load_dwordx4 v[32:35], v187, s[64:65] sc1 nt
	s_add_u32 s64, s64, 0x2000
	s_addc_u32 s65, s65, 0
	ds_bpermute_b32 v174, v188, v186 offset:44
	s_waitcnt vmcnt(32) lgkmcnt(3)
	v_pk_fma_f32 v[160:161], v[36:37], v[168:169], v[160:161] op_sel_hi:[1,0,1]
	v_pk_fma_f32 v[162:163], v[38:39], v[168:169], v[162:163] op_sel_hi:[1,0,1]
	global_load_dwordx4 v[36:39], v187, s[64:65] sc1 nt
	s_add_u32 s64, s64, 0x2000
	s_addc_u32 s65, s65, 0
	ds_bpermute_b32 v168, v188, v186 offset:48
	s_waitcnt vmcnt(32) lgkmcnt(3)
	v_pk_fma_f32 v[164:165], v[40:41], v[170:171], v[164:165] op_sel_hi:[1,0,1]
	v_pk_fma_f32 v[166:167], v[42:43], v[170:171], v[166:167] op_sel_hi:[1,0,1]
	global_load_dwordx4 v[40:43], v187, s[64:65] sc1 nt
	s_add_u32 s64, s64, 0x2000
	s_addc_u32 s65, s65, 0
	ds_bpermute_b32 v170, v188, v186 offset:52
	s_waitcnt vmcnt(32) lgkmcnt(3)
	v_pk_fma_f32 v[160:161], v[44:45], v[172:173], v[160:161] op_sel_hi:[1,0,1]
	v_pk_fma_f32 v[162:163], v[46:47], v[172:173], v[162:163] op_sel_hi:[1,0,1]
	global_load_dwordx4 v[44:47], v187, s[64:65] sc1 nt
	s_add_u32 s64, s64, 0x2000
	s_addc_u32 s65, s65, 0
	ds_bpermute_b32 v172, v188, v186 offset:56
	s_waitcnt vmcnt(32) lgkmcnt(3)
	v_pk_fma_f32 v[164:165], v[48:49], v[174:175], v[164:165] op_sel_hi:[1,0,1]
	v_pk_fma_f32 v[166:167], v[50:51], v[174:175], v[166:167] op_sel_hi:[1,0,1]
	global_load_dwordx4 v[48:51], v187, s[64:65] sc1 nt
	s_add_u32 s64, s64, 0x2000
	s_addc_u32 s65, s65, 0
	ds_bpermute_b32 v174, v188, v186 offset:60
	s_waitcnt vmcnt(32) lgkmcnt(3)
	v_pk_fma_f32 v[160:161], v[52:53], v[168:169], v[160:161] op_sel_hi:[1,0,1]
	v_pk_fma_f32 v[162:163], v[54:55], v[168:169], v[162:163] op_sel_hi:[1,0,1]
	global_load_dwordx4 v[52:55], v187, s[64:65] sc1 nt
	s_add_u32 s64, s64, 0x2000
	s_addc_u32 s65, s65, 0
	ds_bpermute_b32 v168, v188, v186 offset:64
	s_waitcnt vmcnt(32) lgkmcnt(3)
	v_pk_fma_f32 v[164:165], v[56:57], v[170:171], v[164:165] op_sel_hi:[1,0,1]
	v_pk_fma_f32 v[166:167], v[58:59], v[170:171], v[166:167] op_sel_hi:[1,0,1]
	global_load_dwordx4 v[56:59], v187, s[64:65] sc1 nt
	s_add_u32 s64, s64, 0x2000
	s_addc_u32 s65, s65, 0
	ds_bpermute_b32 v170, v188, v186 offset:68
	s_waitcnt vmcnt(32) lgkmcnt(3)
	v_pk_fma_f32 v[160:161], v[60:61], v[172:173], v[160:161] op_sel_hi:[1,0,1]
	v_pk_fma_f32 v[162:163], v[62:63], v[172:173], v[162:163] op_sel_hi:[1,0,1]
	global_load_dwordx4 v[60:63], v187, s[64:65] sc1 nt
	s_add_u32 s64, s64, 0x2000
	s_addc_u32 s65, s65, 0
	ds_bpermute_b32 v172, v188, v186 offset:72
	s_waitcnt vmcnt(32) lgkmcnt(3)
	v_pk_fma_f32 v[164:165], v[64:65], v[174:175], v[164:165] op_sel_hi:[1,0,1]
	v_pk_fma_f32 v[166:167], v[66:67], v[174:175], v[166:167] op_sel_hi:[1,0,1]
	global_load_dwordx4 v[64:67], v187, s[64:65] sc1 nt
	s_add_u32 s64, s64, 0x2000
	s_addc_u32 s65, s65, 0
	s_barrier
; __device__ __forceinline__ void sb_decode_stream(Frame& F, unsigned* qctr, int base, int limit) {
;     ...
;         for (int i = 0; i < 16; ++i) { const float aj = __shfl(a, 32 + 2 * i + half); o4 += aj * B[i]; }
; #pragma unroll
;         for (int i = 0; i < 16; ++i) B[i] = __builtin_nontemporal_load((const f32x4*)(CK + cbn + (size_t)(32 + 2 * i) * stepn));
;         o4.x += __shfl_xor(o4.x, 32); o4.y += __shfl_xor(o4.y, 32); o4.z += __shfl_xor(o4.z, 32); o4.w += __shfl_xor(o4.w, 32);
;         float* P = SSP(S_PART) + ((size_t)bh * DSEG + blk) * DPART;
;         if (half == 0) *(f32x4*)(P + 4 * l32) = o4; if (lane == 0) P[128] = tot;
;         if (!more) break;
;         it = itn; cb = cbn; q4 = q4n;
	ds_bpermute_b32 v174, v188, v186 offset:76
	s_waitcnt vmcnt(32) lgkmcnt(3)
	v_pk_fma_f32 v[160:161], v[68:69], v[168:169], v[160:161] op_sel_hi:[1,0,1]
	v_pk_fma_f32 v[162:163], v[70:71], v[168:169], v[162:163] op_sel_hi:[1,0,1]
	global_load_dwordx4 v[68:71], v187, s[64:65] sc1 nt
	s_add_u32 s64, s64, 0x2000
	s_addc_u32 s65, s65, 0
	ds_bpermute_b32 v168, v188, v186 offset:80
	s_waitcnt vmcnt(32) lgkmcnt(3)
	v_pk_fma_f32 v[164:165], v[72:73], v[170:171], v[164:165] op_sel_hi:[1,0,1]
	v_pk_fma_f32 v[166:167], v[74:75], v[170:171], v[166:167] op_sel_hi:[1,0,1]
	global_load_dwordx4 v[72:75], v187, s[64:65] sc1 nt
	s_add_u32 s64, s64, 0x2000
	s_addc_u32 s65, s65, 0
	ds_bpermute_b32 v170, v188, v186 offset:84
	s_waitcnt vmcnt(32) lgkmcnt(3)
	v_pk_fma_f32 v[160:161], v[76:77], v[172:173], v[160:161] op_sel_hi:[1,0,1]
	v_pk_fma_f32 v[162:163], v[78:79], v[172:173], v[162:163] op_sel_hi:[1,0,1]
	global_load_dwordx4 v[76:79], v187, s[64:65] sc1 nt
	s_add_u32 s64, s64, 0x2000
	s_addc_u32 s65, s65, 0
	ds_bpermute_b32 v172, v188, v186 offset:88
	s_waitcnt vmcnt(32) lgkmcnt(3)
	v_pk_fma_f32 v[164:165], v[80:81], v[174:175], v[164:165] op_sel_hi:[1,0,1]
	v_pk_fma_f32 v[166:167], v[82:83], v[174:175], v[166:167] op_sel_hi:[1,0,1]
	global_load_dwordx4 v[80:83], v187, s[64:65] sc1 nt
	s_add_u32 s64, s64, 0x2000
	s_addc_u32 s65, s65, 0
	ds_bpermute_b32 v174, v188, v186 offset:92
	s_waitcnt vmcnt(32) lgkmcnt(3)
	v_pk_fma_f32 v[160:161], v[84:85], v[168:169], v[160:161] op_sel_hi:[1,0,1]
	v_pk_fma_f32 v[162:163], v[86:87], v[168:169], v[162:163] op_sel_hi:[1,0,1]
	global_load_dwordx4 v[84:87], v187, s[64:65] sc1 nt
	s_add_u32 s64, s64, 0x2000
	s_addc_u32 s65, s65, 0
	ds_bpermute_b32 v168, v188, v186 offset:96
	s_waitcnt vmcnt(32) lgkmcnt(3)
	v_pk_fma_f32 v[164:165], v[88:89], v[170:171], v[164:165] op_sel_hi:[1,0,1]
	v_pk_fma_f32 v[166:167], v[90:91], v[170:171], v[166:167] op_sel_hi:[1,0,1]
	global_load_dwordx4 v[88:91], v187, s[64:65] sc1 nt
	s_add_u32 s64, s64, 0x2000
	s_addc_u32 s65, s65, 0
	ds_bpermute_b32 v170, v188, v186 offset:100
	s_waitcnt vmcnt(32) lgkmcnt(3)
	v_pk_fma_f32 v[160:161], v[92:93], v[172:173], v[160:161] op_sel_hi:[1,0,1]
	v_pk_fma_f32 v[162:163], v[94:95], v[172:173], v[162:163] op_sel_hi:[1,0,1]
	global_load_dwordx4 v[92:95], v187, s[64:65] sc1 nt
	s_add_u32 s64, s64, 0x2000
	s_addc_u32 s65, s65, 0
	ds_bpermute_b32 v172, v188, v186 offset:104
	s_waitcnt vmcnt(32) lgkmcnt(3)
	v_pk_fma_f32 v[164:165], v[96:97], v[174:175], v[164:165] op_sel_hi:[1,0,1]
	v_pk_fma_f32 v[166:167], v[98:99], v[174:175], v[166:167] op_sel_hi:[1,0,1]
	global_load_dwordx4 v[96:99], v187, s[64:65] sc1 nt
	s_add_u32 s64, s64, 0x2000
	s_addc_u32 s65, s65, 0
	ds_bpermute_b32 v174, v188, v186 offset:108
	s_waitcnt vmcnt(32) lgkmcnt(3)
	v_pk_fma_f32 v[160:161], v[100:101], v[168:169], v[160:161] op_sel_hi:[1,0,1]
	v_pk_fma_f32 v[162:163], v[102:103], v[168:169], v[162:163] op_sel_hi:[1,0,1]
	global_load_dwordx4 v[100:103], v187, s[64:65] sc1 nt
	s_add_u32 s64, s64, 0x2000
	s_addc_u32 s65, s65, 0
	ds_bpermute_b32 v168, v188, v186 offset:112
	s_waitcnt vmcnt(32) lgkmcnt(3)
	v_pk_fma_f32 v[164:165], v[104:105], v[170:171], v[164:165] op_sel_hi:[1,0,1]
	v_pk_fma_f32 v[166:167], v[106:107], v[170:171], v[166:167] op_sel_hi:[1,0,1]
	global_load_dwordx4 v[104:107], v187, s[64:65] sc1 nt
	s_add_u32 s64, s64, 0x2000
	s_addc_u32 s65, s65, 0
	ds_bpermute_b32 v170, v188, v186 offset:116
	s_waitcnt vmcnt(32) lgkmcnt(3)
	v_pk_fma_f32 v[160:161], v[108:109], v[172:173], v[160:161] op_sel_hi:[1,0,1]
	v_pk_fma_f32 v[162:163], v[110:111], v[172:173], v[162:163] op_sel_hi:[1,0,1]
	global_load_dwordx4 v[108:111], v187, s[64:65] sc1 nt
	s_add_u32 s64, s64, 0x2000
	s_addc_u32 s65, s65, 0
	ds_bpermute_b32 v172, v188, v186 offset:120
	s_waitcnt vmcnt(32) lgkmcnt(3)
	v_pk_fma_f32 v[164:165], v[112:113], v[174:175], v[164:165] op_sel_hi:[1,0,1]
	v_pk_fma_f32 v[166:167], v[114:115], v[174:175], v[166:167] op_sel_hi:[1,0,1]
	global_load_dwordx4 v[112:115], v187, s[64:65] sc1 nt
	s_add_u32 s64, s64, 0x2000
	s_addc_u32 s65, s65, 0
	ds_bpermute_b32 v174, v188, v186 offset:124
	s_waitcnt vmcnt(32) lgkmcnt(3)
	v_pk_fma_f32 v[160:161], v[116:117], v[168:169], v[160:161] op_sel_hi:[1,0,1]
	v_pk_fma_f32 v[162:163], v[118:119], v[168:169], v[162:163] op_sel_hi:[1,0,1]
	global_load_dwordx4 v[116:119], v187, s[64:65] sc1 nt
	s_add_u32 s64, s64, 0x2000
	s_addc_u32 s65, s65, 0
	s_waitcnt vmcnt(32) lgkmcnt(2)
	v_pk_fma_f32 v[164:165], v[120:121], v[170:171], v[164:165] op_sel_hi:[1,0,1]
	v_pk_fma_f32 v[166:167], v[122:123], v[170:171], v[166:167] op_sel_hi:[1,0,1]
	global_load_dwordx4 v[120:123], v187, s[64:65] sc1 nt
	s_add_u32 s64, s64, 0x2000
	s_addc_u32 s65, s65, 0
	s_waitcnt vmcnt(32) lgkmcnt(1)
	v_pk_fma_f32 v[160:161], v[124:125], v[172:173], v[160:161] op_sel_hi:[1,0,1]
	v_pk_fma_f32 v[162:163], v[126:127], v[172:173], v[162:163] op_sel_hi:[1,0,1]
	global_load_dwordx4 v[124:127], v187, s[64:65] sc1 nt
	s_add_u32 s64, s64, 0x2000
	s_addc_u32 s65, s65, 0
	s_waitcnt vmcnt(32) lgkmcnt(0)
	v_pk_fma_f32 v[164:165], v[128:129], v[174:175], v[164:165] op_sel_hi:[1,0,1]
	v_pk_fma_f32 v[166:167], v[130:131], v[174:175], v[166:167] op_sel_hi:[1,0,1]
	global_load_dwordx4 v[128:131], v187, s[64:65] sc1 nt
	s_add_u32 s64, s64, 0x2000
	s_addc_u32 s65, s65, 0
	s_nop 1
	v_pk_add_f32 v[160:161], v[160:161], v[164:165]
	v_pk_add_f32 v[162:163], v[162:163], v[166:167]
	s_nop 1
	v_mov_b32_e32 v164, v160
	v_mov_b32_e32 v165, v161
	v_mov_b32_e32 v166, v162
	v_mov_b32_e32 v167, v163
	v_permlane32_swap_b32_e32 v160, v164
	v_permlane32_swap_b32_e32 v161, v165
	v_permlane32_swap_b32_e32 v162, v166
	v_permlane32_swap_b32_e32 v163, v167
	v_pk_add_f32 v[160:161], v[160:161], v[164:165]
	v_pk_add_f32 v[162:163], v[162:163], v[166:167]
	s_nop 1
	s_mov_b32 exec_hi, 0
	global_store_dwordx4 v193, v[160:163], s[70:71]
	s_mov_b32 exec_lo, 1
	global_store_dword v189, v183, s[70:71] offset:512
	s_mov_b64 exec, -1
	s_mov_b32 s72, s73
	s_branch .Ldqc_loop
